# strategy 8 continued: the solve block's row-4 LDS read also issued at block entry (four reads in flight, counted lgkmcnt waits)
# baseline (speedup 1.0000x reference)
.LBB0_355:
	s_and_b64 vcc, exec, s[18:19]
	s_cbranch_vccz .LBB0_421
	v_add_u32_e32 v2, v171, v187
	ds_read_b128 v[4:7], v2 offset:272
	v_mov_b32_e32 v2, v188
	ds_read_b128 v[18:21], v2 offset:544
	ds_read_b128 v[22:25], v2 offset:816
	ds_read_b128 v[28:31], v2 offset:1088
	s_waitcnt lgkmcnt(3)
	v_fma_f32 v17, -v195, v4, v196
	s_nop 0
	s_waitcnt lgkmcnt(2)
	v_fma_f32 v3, -v195, v18, v197
	v_fma_f32 v4, -v19, v17, 0
	v_add_f32_e32 v15, v4, v3
	s_nop 0
	s_waitcnt lgkmcnt(1)
	v_fma_f32 v3, -v195, v22, v198
	v_fma_f32 v8, -v17, v23, 0
	v_fma_f32 v9, -v24, v15, 0
	v_add_f32_e32 v3, v8, v3
	v_add_f32_e32 v13, v9, v3
	s_nop 0
	ds_read_b128 v[18:21], v2 offset:1360
	ds_read_b128 v[8:11], v2 offset:1376
	s_waitcnt lgkmcnt(2)
	v_fma_f32 v3, -v195, v28, v199
	v_fma_f32 v4, -v17, v29, 0
	v_fma_f32 v5, -v15, v30, 0
	v_fma_f32 v6, -v31, v13, 0
	v_add_f32_e32 v3, v4, v3
	v_add_f32_e32 v4, v6, v5
	s_waitcnt lgkmcnt(0)
	v_add_f32_e32 v11, v4, v3
	v_fma_f32 v9, -v17, v19, 0
	ds_read_b128 v[4:7], v2 offset:1632
	ds_read_b128 v[22:25], v2 offset:1648
	v_fma_f32 v3, -v195, v18, v200
	v_fma_f32 v10, -v15, v20, 0
	v_fma_f32 v12, -v13, v21, 0
	v_fma_f32 v3, -v8, v11, v3
	v_add_f32_e32 v3, v9, v3
	v_add_f32_e32 v8, v12, v10
	v_add_f32_e32 v9, v8, v3
	s_nop 0
	ds_read_b128 v[18:21], v2 offset:1904
	ds_read_b128 v[28:31], v2 offset:1920
	s_waitcnt lgkmcnt(3)
	v_fma_f32 v3, -v195, v4, v201
	v_fma_f32 v4, -v17, v5, 0
	v_fma_f32 v5, -v15, v6, 0
	v_fma_f32 v6, -v13, v7, 0
	s_waitcnt lgkmcnt(2)
	v_fma_f32 v3, -v11, v22, v3
	v_fma_f32 v4, -v23, v9, v4
	v_add_f32_e32 v3, v4, v3
	v_add_f32_e32 v4, v6, v5
	v_add_f32_e32 v7, v4, v3
	s_waitcnt lgkmcnt(1)
	v_fma_f32 v4, -v17, v19, 0
	ds_read_b128 v[22:25], v2 offset:2176
	ds_read_b128 v[32:35], v2 offset:2192
	v_fma_f32 v3, -v195, v18, v202
	v_fma_f32 v5, -v15, v20, 0
	v_fma_f32 v6, -v13, v21, 0
	s_waitcnt lgkmcnt(2)
	v_fma_f32 v3, -v11, v28, v3
	v_fma_f32 v4, -v9, v29, v4
	v_fma_f32 v5, -v30, v7, v5
	v_add_f32_e32 v3, v4, v3
	v_add_f32_e32 v4, v6, v5
	v_add_f32_e32 v4, v4, v3
	s_waitcnt lgkmcnt(1)
	v_fma_f32 v5, -v17, v23, 0
	ds_read_b128 v[18:21], v2 offset:2448
	ds_read_b128 v[28:31], v2 offset:2464
	ds_read_b128 v[36:39], v2 offset:2480
	v_fma_f32 v3, -v195, v22, v203
	v_fma_f32 v6, -v15, v24, 0
	v_fma_f32 v8, -v13, v25, 0
	s_waitcnt lgkmcnt(3)
	v_fma_f32 v3, -v11, v32, v3
	v_fma_f32 v5, -v9, v33, v5
	v_fma_f32 v6, -v7, v34, v6
	v_fma_f32 v8, -v35, v4, v8
	v_add_f32_e32 v3, v5, v3
	v_add_f32_e32 v5, v8, v6
	v_add_f32_e32 v5, v5, v3
	s_waitcnt lgkmcnt(2)
	v_fma_f32 v6, -v17, v19, 0
	ds_read_b128 v[22:25], v2 offset:2720
	ds_read_b128 v[32:35], v2 offset:2736
	s_waitcnt lgkmcnt(2)
	ds_read_b128 v[38:41], v2 offset:2752
	v_fma_f32 v3, -v195, v18, v204
	v_fma_f32 v8, -v15, v20, 0
	v_fma_f32 v10, -v13, v21, 0
	v_fma_f32 v3, -v11, v28, v3
	v_fma_f32 v6, -v9, v29, v6
	v_fma_f32 v8, -v7, v30, v8
	v_fma_f32 v10, -v4, v31, v10
	v_fma_f32 v3, -v36, v5, v3
	v_add_f32_e32 v3, v6, v3
	v_add_f32_e32 v6, v10, v8
	v_add_f32_e32 v6, v6, v3
	s_waitcnt lgkmcnt(2)
	v_fma_f32 v8, -v17, v23, 0
	ds_read_b128 v[18:21], v2 offset:2992
	ds_read_b128 v[28:31], v2 offset:3008
	s_waitcnt lgkmcnt(2)
	ds_read_b128 v[40:43], v2 offset:3024
	v_fma_f32 v3, -v195, v22, v205
	v_fma_f32 v10, -v15, v24, 0
	v_fma_f32 v12, -v13, v25, 0
	v_fma_f32 v3, -v11, v32, v3
	v_fma_f32 v8, -v9, v33, v8
	v_fma_f32 v10, -v7, v34, v10
	v_fma_f32 v12, -v4, v35, v12
	v_fma_f32 v3, -v5, v38, v3
	v_fma_f32 v8, -v39, v6, v8
	v_add_f32_e32 v3, v8, v3
	v_add_f32_e32 v8, v12, v10
	v_add_f32_e32 v8, v8, v3
	s_waitcnt lgkmcnt(2)
	v_fma_f32 v10, -v17, v19, 0
	ds_read_b128 v[22:25], v2 offset:3264
	ds_read_b128 v[32:35], v2 offset:3280
	ds_read_b128 v[36:39], v2 offset:3296
	v_fma_f32 v3, -v195, v18, v206
	v_fma_f32 v12, -v15, v20, 0
	v_fma_f32 v14, -v13, v21, 0
	s_waitcnt lgkmcnt(4)
	v_fma_f32 v3, -v11, v28, v3
	v_fma_f32 v10, -v9, v29, v10
	v_fma_f32 v12, -v7, v30, v12
	v_fma_f32 v14, -v4, v31, v14
	s_waitcnt lgkmcnt(3)
	v_fma_f32 v3, -v5, v40, v3
	v_fma_f32 v10, -v6, v41, v10
	v_fma_f32 v12, -v42, v8, v12
	v_add_f32_e32 v3, v10, v3
	v_add_f32_e32 v10, v14, v12
	v_add_f32_e32 v10, v10, v3
	s_waitcnt lgkmcnt(2)
	v_fma_f32 v12, -v17, v23, 0
	ds_read_b128 v[18:21], v2 offset:3536
	ds_read_b128 v[28:31], v2 offset:3552
	ds_read_b128 v[40:43], v2 offset:3568
	ds_read_b128 v[44:47], v2 offset:3584
	v_fma_f32 v3, -v195, v22, v207
	v_fma_f32 v14, -v15, v24, 0
	v_fma_f32 v16, -v13, v25, 0
	s_waitcnt lgkmcnt(5)
	v_fma_f32 v3, -v11, v32, v3
	v_fma_f32 v12, -v9, v33, v12
	v_fma_f32 v14, -v7, v34, v14
	v_fma_f32 v16, -v4, v35, v16
	s_waitcnt lgkmcnt(4)
	v_fma_f32 v3, -v5, v36, v3
	v_fma_f32 v12, -v6, v37, v12
	v_fma_f32 v14, -v8, v38, v14
	v_fma_f32 v16, -v39, v10, v16
	v_add_f32_e32 v3, v12, v3
	v_add_f32_e32 v12, v16, v14
	v_add_f32_e32 v12, v12, v3
	s_waitcnt lgkmcnt(3)
	v_fma_f32 v14, -v17, v19, 0
	ds_read_b128 v[22:25], v2 offset:3808
	ds_read_b128 v[32:35], v2 offset:3824
	ds_read_b128 v[36:39], v2 offset:3840
	s_waitcnt lgkmcnt(3)
	ds_read_b128 v[46:49], v2 offset:3856
	v_fma_f32 v3, -v195, v18, v208
	v_fma_f32 v16, -v15, v20, 0
	v_fma_f32 v18, -v13, v21, 0
	v_fma_f32 v3, -v11, v28, v3
	v_fma_f32 v14, -v9, v29, v14
	v_fma_f32 v16, -v7, v30, v16
	v_fma_f32 v18, -v4, v31, v18
	v_fma_f32 v3, -v5, v40, v3
	v_fma_f32 v14, -v6, v41, v14
	v_fma_f32 v16, -v8, v42, v16
	v_fma_f32 v18, -v10, v43, v18
	v_fma_f32 v3, -v44, v12, v3
	v_add_f32_e32 v3, v14, v3
	v_add_f32_e32 v14, v18, v16
	v_add_f32_e32 v14, v14, v3
	s_waitcnt lgkmcnt(3)
	v_fma_f32 v16, -v17, v23, 0
	ds_read_b128 v[18:21], v2 offset:4080
	ds_read_b128 v[28:31], v2 offset:4096
	ds_read_b128 v[40:43], v2 offset:4112
	s_waitcnt lgkmcnt(3)
	ds_read_b128 v[48:51], v2 offset:4128
	v_fma_f32 v3, -v195, v22, v209
	v_fma_f32 v22, -v15, v24, 0
	v_fma_f32 v23, -v13, v25, 0
	v_fma_f32 v3, -v11, v32, v3
	v_fma_f32 v16, -v9, v33, v16
	v_fma_f32 v22, -v7, v34, v22
	v_fma_f32 v23, -v4, v35, v23
	v_fma_f32 v3, -v5, v36, v3
	v_fma_f32 v16, -v6, v37, v16
	v_fma_f32 v22, -v8, v38, v22
	v_fma_f32 v23, -v10, v39, v23
	v_fma_f32 v3, -v12, v46, v3
	v_fma_f32 v16, -v47, v14, v16
	v_add_f32_e32 v3, v16, v3
	v_add_f32_e32 v16, v23, v22
	v_add_f32_e32 v16, v16, v3
	s_nop 0
	ds_read_b128 v[22:25], v2 offset:4352
	ds_read_b128 v[32:35], v2 offset:4368
	ds_read_b128 v[36:39], v2 offset:4384
	ds_read_b128 v[44:47], v2 offset:4400
	s_waitcnt lgkmcnt(7)
	v_fma_f32 v3, -v195, v18, v210
	v_fma_f32 v18, -v17, v19, 0
	v_fma_f32 v19, -v15, v20, 0
	v_fma_f32 v20, -v13, v21, 0
	s_waitcnt lgkmcnt(6)
	v_fma_f32 v3, -v11, v28, v3
	v_fma_f32 v18, -v9, v29, v18
	v_fma_f32 v19, -v7, v30, v19
	v_fma_f32 v20, -v4, v31, v20
	s_waitcnt lgkmcnt(5)
	v_fma_f32 v3, -v5, v40, v3
	v_fma_f32 v18, -v6, v41, v18
	v_fma_f32 v19, -v8, v42, v19
	v_fma_f32 v20, -v10, v43, v20
	s_waitcnt lgkmcnt(4)
	v_fma_f32 v3, -v12, v48, v3
	v_fma_f32 v18, -v14, v49, v18
	v_fma_f32 v19, -v50, v16, v19
	v_add_f32_e32 v3, v18, v3
	v_add_f32_e32 v18, v20, v19
	v_add_f32_e32 v18, v18, v3
	s_waitcnt lgkmcnt(3)
	v_fma_f32 v19, -v17, v23, 0
	ds_read_b128 v[28:31], v2 offset:4624
	ds_read_b128 v[40:43], v2 offset:4640
	ds_read_b128 v[48:51], v2 offset:4656
	ds_read_b128 v[52:55], v2 offset:4672
	ds_read_b128 v[56:59], v2 offset:4688
	v_fma_f32 v3, -v195, v22, v211
	v_fma_f32 v20, -v15, v24, 0
	v_fma_f32 v21, -v13, v25, 0
	s_waitcnt lgkmcnt(7)
	v_fma_f32 v3, -v11, v32, v3
	v_fma_f32 v19, -v9, v33, v19
	v_fma_f32 v20, -v7, v34, v20
	v_fma_f32 v21, -v4, v35, v21
	s_waitcnt lgkmcnt(6)
	v_fma_f32 v3, -v5, v36, v3
	v_fma_f32 v19, -v6, v37, v19
	v_fma_f32 v20, -v8, v38, v20
	v_fma_f32 v21, -v10, v39, v21
	s_waitcnt lgkmcnt(5)
	v_fma_f32 v3, -v12, v44, v3
	v_fma_f32 v19, -v14, v45, v19
	v_fma_f32 v20, -v16, v46, v20
	v_fma_f32 v21, -v47, v18, v21
	v_add_f32_e32 v3, v19, v3
	v_add_f32_e32 v19, v21, v20
	v_add_f32_e32 v19, v19, v3
	s_waitcnt lgkmcnt(4)
	v_fma_f32 v20, -v17, v29, 0
	ds_read_b128 v[22:25], v2 offset:4896
	ds_read_b128 v[32:35], v2 offset:4912
	ds_read_b128 v[36:39], v2 offset:4928
	ds_read_b128 v[44:47], v2 offset:4944
	s_waitcnt lgkmcnt(4)
	ds_read_b128 v[58:61], v2 offset:4960
	v_fma_f32 v3, -v195, v28, v212
	v_fma_f32 v21, -v15, v30, 0
	v_fma_f32 v27, -v13, v31, 0
	v_fma_f32 v3, -v11, v40, v3
	v_fma_f32 v20, -v9, v41, v20
	v_fma_f32 v21, -v7, v42, v21
	v_fma_f32 v27, -v4, v43, v27
	v_fma_f32 v3, -v5, v48, v3
	v_fma_f32 v20, -v6, v49, v20
	v_fma_f32 v21, -v8, v50, v21
	v_fma_f32 v27, -v10, v51, v27
	v_fma_f32 v3, -v12, v52, v3
	v_fma_f32 v20, -v14, v53, v20
	v_fma_f32 v21, -v16, v54, v21
	v_fma_f32 v27, -v18, v55, v27
	v_fma_f32 v3, -v56, v19, v3
	v_add_f32_e32 v3, v20, v3
	v_add_f32_e32 v20, v27, v21
	v_add_f32_e32 v20, v20, v3
	s_waitcnt lgkmcnt(4)
	v_fma_f32 v21, -v17, v23, 0
	ds_read_b128 v[28:31], v2 offset:5168
	ds_read_b128 v[40:43], v2 offset:5184
	ds_read_b128 v[48:51], v2 offset:5200
	ds_read_b128 v[52:55], v2 offset:5216
	s_waitcnt lgkmcnt(4)
	ds_read_b128 v[60:63], v2 offset:5232
	v_fma_f32 v3, -v195, v22, v213
	v_fma_f32 v22, -v15, v24, 0
	v_fma_f32 v23, -v13, v25, 0
	v_fma_f32 v3, -v11, v32, v3
	v_fma_f32 v21, -v9, v33, v21
	v_fma_f32 v22, -v7, v34, v22
	v_fma_f32 v23, -v4, v35, v23
	v_fma_f32 v3, -v5, v36, v3
	v_fma_f32 v21, -v6, v37, v21
	v_fma_f32 v22, -v8, v38, v22
	v_fma_f32 v23, -v10, v39, v23
	v_fma_f32 v3, -v12, v44, v3
	v_fma_f32 v21, -v14, v45, v21
	v_fma_f32 v22, -v16, v46, v22
	v_fma_f32 v23, -v18, v47, v23
	v_fma_f32 v3, -v19, v58, v3
	v_fma_f32 v21, -v59, v20, v21
	v_add_f32_e32 v3, v21, v3
	v_add_f32_e32 v21, v23, v22
	v_add_f32_e32 v21, v21, v3
	s_waitcnt lgkmcnt(4)
	v_fma_f32 v22, -v17, v29, 0
	ds_read_b128 v[32:35], v2 offset:5440
	ds_read_b128 v[36:39], v2 offset:5456
	ds_read_b128 v[44:47], v2 offset:5472
	ds_read_b128 v[56:59], v2 offset:5488
	ds_read_b128 v[64:67], v2 offset:5504
	v_fma_f32 v3, -v195, v28, v214
	v_fma_f32 v23, -v15, v30, 0
	v_fma_f32 v24, -v13, v31, 0
	s_waitcnt lgkmcnt(8)
	v_fma_f32 v3, -v11, v40, v3
	v_fma_f32 v22, -v9, v41, v22
	v_fma_f32 v23, -v7, v42, v23
	v_fma_f32 v24, -v4, v43, v24
	s_waitcnt lgkmcnt(7)
	v_fma_f32 v3, -v5, v48, v3
	v_fma_f32 v22, -v6, v49, v22
	v_fma_f32 v23, -v8, v50, v23
	v_fma_f32 v24, -v10, v51, v24
	s_waitcnt lgkmcnt(6)
	v_fma_f32 v3, -v12, v52, v3
	v_fma_f32 v22, -v14, v53, v22
	v_fma_f32 v23, -v16, v54, v23
	v_fma_f32 v24, -v18, v55, v24
	s_waitcnt lgkmcnt(5)
	v_fma_f32 v3, -v19, v60, v3
	v_fma_f32 v22, -v20, v61, v22
	v_fma_f32 v23, -v62, v21, v23
	v_add_f32_e32 v3, v22, v3
	v_add_f32_e32 v22, v24, v23
	v_add_f32_e32 v22, v22, v3
	s_waitcnt lgkmcnt(4)
	v_fma_f32 v23, -v17, v33, 0
	ds_read_b128 v[28:31], v2 offset:5712
	ds_read_b128 v[40:43], v2 offset:5728
	ds_read_b128 v[48:51], v2 offset:5744
	ds_read_b128 v[52:55], v2 offset:5760
	ds_read_b128 v[60:63], v2 offset:5776
	ds_read_b128 v[68:71], v2 offset:5792
	v_fma_f32 v3, -v195, v32, v215
	v_fma_f32 v24, -v15, v34, 0
	v_fma_f32 v25, -v13, v35, 0
	s_waitcnt lgkmcnt(9)
	v_fma_f32 v3, -v11, v36, v3
	v_fma_f32 v23, -v9, v37, v23
	v_fma_f32 v24, -v7, v38, v24
	v_fma_f32 v25, -v4, v39, v25
	s_waitcnt lgkmcnt(8)
	v_fma_f32 v3, -v5, v44, v3
	v_fma_f32 v23, -v6, v45, v23
	v_fma_f32 v24, -v8, v46, v24
	v_fma_f32 v25, -v10, v47, v25
	s_waitcnt lgkmcnt(7)
	v_fma_f32 v3, -v12, v56, v3
	v_fma_f32 v23, -v14, v57, v23
	v_fma_f32 v24, -v16, v58, v24
	v_fma_f32 v25, -v18, v59, v25
	s_waitcnt lgkmcnt(6)
	v_fma_f32 v3, -v19, v64, v3
	v_fma_f32 v23, -v20, v65, v23
	v_fma_f32 v24, -v21, v66, v24
	v_fma_f32 v25, -v67, v22, v25
	v_add_f32_e32 v3, v23, v3
	v_add_f32_e32 v23, v25, v24
	v_add_f32_e32 v23, v23, v3
	s_waitcnt lgkmcnt(5)
	v_fma_f32 v24, -v17, v29, 0
	ds_read_b128 v[32:35], v2 offset:5984
	ds_read_b128 v[36:39], v2 offset:6000
	ds_read_b128 v[44:47], v2 offset:6016
	ds_read_b128 v[56:59], v2 offset:6032
	ds_read_b128 v[64:67], v2 offset:6048
	s_waitcnt lgkmcnt(5)
	ds_read_b128 v[70:73], v2 offset:6064
	v_fma_f32 v3, -v195, v28, v216
	v_fma_f32 v25, -v15, v30, 0
	v_fma_f32 v27, -v13, v31, 0
	v_fma_f32 v3, -v11, v40, v3
	v_fma_f32 v24, -v9, v41, v24
	v_fma_f32 v25, -v7, v42, v25
	v_fma_f32 v27, -v4, v43, v27
	v_fma_f32 v3, -v5, v48, v3
	v_fma_f32 v24, -v6, v49, v24
	v_fma_f32 v25, -v8, v50, v25
	v_fma_f32 v27, -v10, v51, v27
	v_fma_f32 v3, -v12, v52, v3
	v_fma_f32 v24, -v14, v53, v24
	v_fma_f32 v25, -v16, v54, v25
	v_fma_f32 v27, -v18, v55, v27
	v_fma_f32 v3, -v19, v60, v3
	v_fma_f32 v24, -v20, v61, v24
	v_fma_f32 v25, -v21, v62, v25
	v_fma_f32 v27, -v22, v63, v27
	v_fma_f32 v3, -v68, v23, v3
	v_add_f32_e32 v3, v24, v3
	v_add_f32_e32 v24, v27, v25
	v_add_f32_e32 v24, v24, v3
	s_waitcnt lgkmcnt(5)
	v_fma_f32 v25, -v17, v33, 0
	ds_read_b128 v[28:31], v2 offset:6256
	ds_read_b128 v[40:43], v2 offset:6272
	ds_read_b128 v[48:51], v2 offset:6288
	ds_read_b128 v[52:55], v2 offset:6304
	ds_read_b128 v[60:63], v2 offset:6320
	s_waitcnt lgkmcnt(5)
	ds_read_b128 v[72:75], v2 offset:6336
	v_fma_f32 v3, -v195, v32, v217
	v_fma_f32 v27, -v15, v34, 0
	v_fma_f32 v32, -v13, v35, 0
	v_fma_f32 v3, -v11, v36, v3
	v_fma_f32 v25, -v9, v37, v25
	v_fma_f32 v27, -v7, v38, v27
	v_fma_f32 v32, -v4, v39, v32
	v_fma_f32 v3, -v5, v44, v3
	v_fma_f32 v25, -v6, v45, v25
	v_fma_f32 v27, -v8, v46, v27
	v_fma_f32 v32, -v10, v47, v32
	v_fma_f32 v3, -v12, v56, v3
	v_fma_f32 v25, -v14, v57, v25
	v_fma_f32 v27, -v16, v58, v27
	v_fma_f32 v32, -v18, v59, v32
	v_fma_f32 v3, -v19, v64, v3
	v_fma_f32 v25, -v20, v65, v25
	v_fma_f32 v27, -v21, v66, v27
	v_fma_f32 v32, -v22, v67, v32
	v_fma_f32 v3, -v23, v70, v3
	v_fma_f32 v25, -v71, v24, v25
	v_add_f32_e32 v3, v25, v3
	v_add_f32_e32 v25, v32, v27
	v_add_f32_e32 v25, v25, v3
	s_waitcnt lgkmcnt(5)
	v_fma_f32 v27, -v17, v29, 0
	ds_read_b128 v[32:35], v2 offset:6528
	ds_read_b128 v[36:39], v2 offset:6544
	ds_read_b128 v[44:47], v2 offset:6560
	ds_read_b128 v[56:59], v2 offset:6576
	ds_read_b128 v[64:67], v2 offset:6592
	ds_read_b128 v[68:71], v2 offset:6608
	v_fma_f32 v3, -v195, v28, v218
	v_fma_f32 v28, -v15, v30, 0
	v_fma_f32 v29, -v13, v31, 0
	s_waitcnt lgkmcnt(10)
	v_fma_f32 v3, -v11, v40, v3
	v_fma_f32 v27, -v9, v41, v27
	v_fma_f32 v28, -v7, v42, v28
	v_fma_f32 v29, -v4, v43, v29
	s_waitcnt lgkmcnt(9)
	v_fma_f32 v3, -v5, v48, v3
	v_fma_f32 v27, -v6, v49, v27
	v_fma_f32 v28, -v8, v50, v28
	v_fma_f32 v29, -v10, v51, v29
	s_waitcnt lgkmcnt(8)
	v_fma_f32 v3, -v12, v52, v3
	v_fma_f32 v27, -v14, v53, v27
	v_fma_f32 v28, -v16, v54, v28
	v_fma_f32 v29, -v18, v55, v29
	s_waitcnt lgkmcnt(7)
	v_fma_f32 v3, -v19, v60, v3
	v_fma_f32 v27, -v20, v61, v27
	v_fma_f32 v28, -v21, v62, v28
	v_fma_f32 v29, -v22, v63, v29
	s_waitcnt lgkmcnt(6)
	v_fma_f32 v3, -v23, v72, v3
	v_fma_f32 v27, -v24, v73, v27
	v_fma_f32 v28, -v74, v25, v28
	v_add_f32_e32 v3, v27, v3
	v_add_f32_e32 v27, v29, v28
	v_add_f32_e32 v27, v27, v3
	s_waitcnt lgkmcnt(5)
	v_fma_f32 v28, -v17, v33, 0
	ds_read_b128 v[40:43], v2 offset:6800
	ds_read_b128 v[48:51], v2 offset:6816
	ds_read_b128 v[52:55], v2 offset:6832
	ds_read_b128 v[60:63], v2 offset:6848
	ds_read_b128 v[72:75], v2 offset:6864
	ds_read_b128 v[76:79], v2 offset:6880
	ds_read_b128 v[140:143], v2 offset:6896
	v_fma_f32 v3, -v195, v32, v219
	v_fma_f32 v29, -v15, v34, 0
	v_fma_f32 v30, -v13, v35, 0
	s_waitcnt lgkmcnt(11)
	v_fma_f32 v3, -v11, v36, v3
	v_fma_f32 v28, -v9, v37, v28
	v_fma_f32 v29, -v7, v38, v29
	v_fma_f32 v30, -v4, v39, v30
	s_waitcnt lgkmcnt(10)
	v_fma_f32 v3, -v5, v44, v3
	v_fma_f32 v28, -v6, v45, v28
	v_fma_f32 v29, -v8, v46, v29
	v_fma_f32 v30, -v10, v47, v30
	s_waitcnt lgkmcnt(9)
	v_fma_f32 v3, -v12, v56, v3
	v_fma_f32 v28, -v14, v57, v28
	v_fma_f32 v29, -v16, v58, v29
	v_fma_f32 v30, -v18, v59, v30
	s_waitcnt lgkmcnt(8)
	v_fma_f32 v3, -v19, v64, v3
	v_fma_f32 v28, -v20, v65, v28
	v_fma_f32 v29, -v21, v66, v29
	v_fma_f32 v30, -v22, v67, v30
	s_waitcnt lgkmcnt(7)
	v_fma_f32 v3, -v23, v68, v3
	v_fma_f32 v28, -v24, v69, v28
	v_fma_f32 v29, -v25, v70, v29
	v_fma_f32 v30, -v71, v27, v30
	v_add_f32_e32 v3, v28, v3
	v_add_f32_e32 v28, v30, v29
	v_add_f32_e32 v28, v28, v3
	s_waitcnt lgkmcnt(6)
	v_fma_f32 v29, -v17, v41, 0
	ds_read_b128 v[30:33], v2 offset:7072
	ds_read_b128 v[34:37], v2 offset:7088
	ds_read_b128 v[44:47], v2 offset:7104
	ds_read_b128 v[56:59], v2 offset:7120
	ds_read_b128 v[64:67], v2 offset:7136
	ds_read_b128 v[68:71], v2 offset:7152
	s_waitcnt lgkmcnt(6)
	ds_read_b128 v[142:145], v2 offset:7168
	v_fma_f32 v3, -v195, v40, v220
	v_fma_f32 v38, -v15, v42, 0
	v_fma_f32 v39, -v13, v43, 0
	v_fma_f32 v3, -v11, v48, v3
	v_fma_f32 v29, -v9, v49, v29
	v_fma_f32 v38, -v7, v50, v38
	v_fma_f32 v39, -v4, v51, v39
	v_fma_f32 v3, -v5, v52, v3
	v_fma_f32 v29, -v6, v53, v29
	v_fma_f32 v38, -v8, v54, v38
	v_fma_f32 v39, -v10, v55, v39
	v_fma_f32 v3, -v12, v60, v3
	v_fma_f32 v29, -v14, v61, v29
	v_fma_f32 v38, -v16, v62, v38
	v_fma_f32 v39, -v18, v63, v39
	v_fma_f32 v3, -v19, v72, v3
	v_fma_f32 v29, -v20, v73, v29
	v_fma_f32 v38, -v21, v74, v38
	v_fma_f32 v39, -v22, v75, v39
	v_fma_f32 v3, -v23, v76, v3
	v_fma_f32 v29, -v24, v77, v29
	v_fma_f32 v38, -v25, v78, v38
	v_fma_f32 v39, -v27, v79, v39
	v_fma_f32 v3, -v140, v28, v3
	v_add_f32_e32 v3, v29, v3
	v_add_f32_e32 v29, v39, v38
	v_add_f32_e32 v29, v29, v3
	s_nop 0
	ds_read_b128 v[38:41], v2 offset:7344
	ds_read_b128 v[48:51], v2 offset:7360
	ds_read_b128 v[52:55], v2 offset:7376
	ds_read_b128 v[60:63], v2 offset:7392
	ds_read_b128 v[72:75], v2 offset:7408
	ds_read_b128 v[76:79], v2 offset:7424
	s_waitcnt lgkmcnt(6)
	ds_read_b128 v[144:147], v2 offset:7440
	v_fma_f32 v3, -v195, v30, v221
	v_fma_f32 v30, -v17, v31, 0
	v_fma_f32 v31, -v15, v32, 0
	v_fma_f32 v32, -v13, v33, 0
	v_fma_f32 v3, -v11, v34, v3
	v_fma_f32 v30, -v9, v35, v30
	v_fma_f32 v31, -v7, v36, v31
	v_fma_f32 v32, -v4, v37, v32
	v_fma_f32 v3, -v5, v44, v3
	v_fma_f32 v30, -v6, v45, v30
	v_fma_f32 v31, -v8, v46, v31
	v_fma_f32 v32, -v10, v47, v32
	v_fma_f32 v3, -v12, v56, v3
	v_fma_f32 v30, -v14, v57, v30
	v_fma_f32 v31, -v16, v58, v31
	v_fma_f32 v32, -v18, v59, v32
	v_fma_f32 v3, -v19, v64, v3
	v_fma_f32 v30, -v20, v65, v30
	v_fma_f32 v31, -v21, v66, v31
	v_fma_f32 v32, -v22, v67, v32
	v_fma_f32 v3, -v23, v68, v3
	v_fma_f32 v30, -v24, v69, v30
	v_fma_f32 v31, -v25, v70, v31
	v_fma_f32 v32, -v27, v71, v32
	v_fma_f32 v3, -v28, v142, v3
	v_fma_f32 v30, -v143, v29, v30
	v_add_f32_e32 v3, v30, v3
	v_add_f32_e32 v30, v32, v31
	v_add_f32_e32 v30, v30, v3
	s_waitcnt lgkmcnt(6)
	v_fma_f32 v31, -v17, v39, 0
	ds_read_b128 v[32:35], v2 offset:7616
	ds_read_b128 v[42:45], v2 offset:7632
	ds_read_b128 v[56:59], v2 offset:7648
	ds_read_b128 v[64:67], v2 offset:7664
	ds_read_b128 v[68:71], v2 offset:7680
	ds_read_b128 v[140:143], v2 offset:7696
	ds_read_b128 v[148:151], v2 offset:7712
	v_fma_f32 v3, -v195, v38, v222
	v_fma_f32 v36, -v15, v40, 0
	v_fma_f32 v37, -v13, v41, 0
	s_waitcnt lgkmcnt(12)
	v_fma_f32 v3, -v11, v48, v3
	v_fma_f32 v31, -v9, v49, v31
	v_fma_f32 v36, -v7, v50, v36
	v_fma_f32 v37, -v4, v51, v37
	s_waitcnt lgkmcnt(11)
	v_fma_f32 v3, -v5, v52, v3
	v_fma_f32 v31, -v6, v53, v31
	v_fma_f32 v36, -v8, v54, v36
	v_fma_f32 v37, -v10, v55, v37
	s_waitcnt lgkmcnt(10)
	v_fma_f32 v3, -v12, v60, v3
	v_fma_f32 v31, -v14, v61, v31
	v_fma_f32 v36, -v16, v62, v36
	v_fma_f32 v37, -v18, v63, v37
	s_waitcnt lgkmcnt(9)
	v_fma_f32 v3, -v19, v72, v3
	v_fma_f32 v31, -v20, v73, v31
	v_fma_f32 v36, -v21, v74, v36
	v_fma_f32 v37, -v22, v75, v37
	s_waitcnt lgkmcnt(8)
	v_fma_f32 v3, -v23, v76, v3
	v_fma_f32 v31, -v24, v77, v31
	v_fma_f32 v36, -v25, v78, v36
	v_fma_f32 v37, -v27, v79, v37
	s_waitcnt lgkmcnt(7)
	v_fma_f32 v3, -v28, v144, v3
	v_fma_f32 v31, -v29, v145, v31
	v_fma_f32 v36, -v146, v30, v36
	v_add_f32_e32 v3, v31, v3
	v_add_f32_e32 v31, v37, v36
	v_add_f32_e32 v31, v31, v3
	s_nop 0
	ds_read_b128 v[36:39], v2 offset:7888
	ds_read_b128 v[46:49], v2 offset:7904
	ds_read_b128 v[50:53], v2 offset:7920
	ds_read_b128 v[60:63], v2 offset:7936
	ds_read_b128 v[72:75], v2 offset:7952
	ds_read_b128 v[76:79], v2 offset:7968
	ds_read_b128 v[144:147], v2 offset:7984
	ds_read_b128 v[152:155], v2 offset:8000
	s_waitcnt lgkmcnt(14)
	v_fma_f32 v3, -v195, v32, v223
	v_fma_f32 v32, -v17, v33, 0
	v_fma_f32 v33, -v15, v34, 0
	v_fma_f32 v34, -v13, v35, 0
	s_waitcnt lgkmcnt(13)
	v_fma_f32 v3, -v11, v42, v3
	v_fma_f32 v32, -v9, v43, v32
	v_fma_f32 v33, -v7, v44, v33
	v_fma_f32 v34, -v4, v45, v34
	s_waitcnt lgkmcnt(12)
	v_fma_f32 v3, -v5, v56, v3
	v_fma_f32 v32, -v6, v57, v32
	v_fma_f32 v33, -v8, v58, v33
	v_fma_f32 v34, -v10, v59, v34
	s_waitcnt lgkmcnt(11)
	v_fma_f32 v3, -v12, v64, v3
	v_fma_f32 v32, -v14, v65, v32
	v_fma_f32 v33, -v16, v66, v33
	v_fma_f32 v34, -v18, v67, v34
	s_waitcnt lgkmcnt(10)
	v_fma_f32 v3, -v19, v68, v3
	v_fma_f32 v32, -v20, v69, v32
	v_fma_f32 v33, -v21, v70, v33
	v_fma_f32 v34, -v22, v71, v34
	s_waitcnt lgkmcnt(9)
	v_fma_f32 v3, -v23, v140, v3
	v_fma_f32 v32, -v24, v141, v32
	v_fma_f32 v33, -v25, v142, v33
	v_fma_f32 v34, -v27, v143, v34
	s_waitcnt lgkmcnt(8)
	v_fma_f32 v3, -v28, v148, v3
	v_fma_f32 v32, -v29, v149, v32
	v_fma_f32 v33, -v30, v150, v33
	v_fma_f32 v34, -v151, v31, v34
	v_add_f32_e32 v3, v32, v3
	v_add_f32_e32 v32, v34, v33
	v_add_f32_e32 v32, v32, v3
	s_waitcnt lgkmcnt(7)
	v_fma_f32 v33, -v17, v37, 0
	ds_read_b128 v[40:43], v2 offset:8160
	ds_read_b128 v[54:57], v2 offset:8176
	ds_read_b128 v[64:67], v2 offset:8192
	ds_read_b128 v[68:71], v2 offset:8208
	ds_read_b128 v[140:143], v2 offset:8224
	ds_read_b128 v[148:151], v2 offset:8240
	s_waitcnt lgkmcnt(6)
	ds_read_b128 v[154:157], v2 offset:8256
	ds_read_b128 v[158:161], v2 offset:8272
	v_fma_f32 v3, -v195, v36, v224
	v_fma_f32 v34, -v15, v38, 0
	v_fma_f32 v35, -v13, v39, 0
	v_fma_f32 v3, -v11, v46, v3
	v_fma_f32 v33, -v9, v47, v33
	v_fma_f32 v34, -v7, v48, v34
	v_fma_f32 v35, -v4, v49, v35
	v_fma_f32 v3, -v5, v50, v3
	v_fma_f32 v33, -v6, v51, v33
	v_fma_f32 v34, -v8, v52, v34
	v_fma_f32 v35, -v10, v53, v35
	v_fma_f32 v3, -v12, v60, v3
	v_fma_f32 v33, -v14, v61, v33
	v_fma_f32 v34, -v16, v62, v34
	v_fma_f32 v35, -v18, v63, v35
	v_fma_f32 v3, -v19, v72, v3
	v_fma_f32 v33, -v20, v73, v33
	v_fma_f32 v34, -v21, v74, v34
	v_fma_f32 v35, -v22, v75, v35
	v_fma_f32 v3, -v23, v76, v3
	v_fma_f32 v33, -v24, v77, v33
	v_fma_f32 v34, -v25, v78, v34
	v_fma_f32 v35, -v27, v79, v35
	v_fma_f32 v3, -v28, v144, v3
	v_fma_f32 v33, -v29, v145, v33
	v_fma_f32 v34, -v30, v146, v34
	v_fma_f32 v35, -v31, v147, v35
	v_fma_f32 v3, -v152, v32, v3
	v_add_f32_e32 v3, v33, v3
	v_add_f32_e32 v33, v35, v34
	v_add_f32_e32 v33, v33, v3
	s_waitcnt lgkmcnt(7)
	v_fma_f32 v34, -v17, v41, 0
	ds_read_b128 v[36:39], v2 offset:8432
	ds_read_b128 v[44:47], v2 offset:8448
	ds_read_b128 v[48:51], v2 offset:8464
	ds_read_b128 v[58:61], v2 offset:8480
	ds_read_b128 v[72:75], v2 offset:8496
	ds_read_b128 v[76:79], v2 offset:8512
	ds_read_b128 v[144:147], v2 offset:8528
	s_waitcnt lgkmcnt(7)
	ds_read_b128 v[160:163], v2 offset:8544
	v_fma_f32 v3, -v195, v40, v225
	v_fma_f32 v35, -v15, v42, 0
	v_fma_f32 v40, -v13, v43, 0
	v_fma_f32 v3, -v11, v54, v3
	v_fma_f32 v34, -v9, v55, v34
	v_fma_f32 v35, -v7, v56, v35
	v_fma_f32 v40, -v4, v57, v40
	v_fma_f32 v3, -v5, v64, v3
	v_fma_f32 v34, -v6, v65, v34
	v_fma_f32 v35, -v8, v66, v35
	v_fma_f32 v40, -v10, v67, v40
	v_fma_f32 v3, -v12, v68, v3
	v_fma_f32 v34, -v14, v69, v34
	v_fma_f32 v35, -v16, v70, v35
	v_fma_f32 v40, -v18, v71, v40
	v_fma_f32 v3, -v19, v140, v3
	v_fma_f32 v34, -v20, v141, v34
	v_fma_f32 v35, -v21, v142, v35
	v_fma_f32 v40, -v22, v143, v40
	v_fma_f32 v3, -v23, v148, v3
	v_fma_f32 v34, -v24, v149, v34
	v_fma_f32 v35, -v25, v150, v35
	v_fma_f32 v40, -v27, v151, v40
	v_fma_f32 v3, -v28, v154, v3
	v_fma_f32 v34, -v29, v155, v34
	v_fma_f32 v35, -v30, v156, v35
	v_fma_f32 v40, -v31, v157, v40
	v_fma_f32 v3, -v32, v158, v3
	v_fma_f32 v34, -v159, v33, v34
	v_add_f32_e32 v3, v34, v3
	v_add_f32_e32 v34, v40, v35
	v_add_f32_e32 v34, v34, v3
	s_waitcnt lgkmcnt(7)
	v_fma_f32 v3, -v17, v37, 0
	v_fma_f32 v2, -v195, v36, v226
	v_fma_f32 v35, -v15, v38, 0
	v_fma_f32 v36, -v13, v39, 0
	s_waitcnt lgkmcnt(6)
	v_fma_f32 v2, -v11, v44, v2
	v_fma_f32 v3, -v9, v45, v3
	v_fma_f32 v35, -v7, v46, v35
	v_fma_f32 v36, -v4, v47, v36
	s_waitcnt lgkmcnt(5)
	v_fma_f32 v2, -v5, v48, v2
	v_fma_f32 v3, -v6, v49, v3
	v_fma_f32 v35, -v8, v50, v35
	v_fma_f32 v36, -v10, v51, v36
	s_waitcnt lgkmcnt(4)
	v_fma_f32 v2, -v12, v58, v2
	v_fma_f32 v3, -v14, v59, v3
	v_fma_f32 v35, -v16, v60, v35
	v_fma_f32 v36, -v18, v61, v36
	s_waitcnt lgkmcnt(3)
	v_fma_f32 v2, -v19, v72, v2
	v_fma_f32 v3, -v20, v73, v3
	v_fma_f32 v35, -v21, v74, v35
	v_fma_f32 v36, -v22, v75, v36
	s_waitcnt lgkmcnt(2)
	v_fma_f32 v2, -v23, v76, v2
	v_fma_f32 v3, -v24, v77, v3
	v_fma_f32 v35, -v25, v78, v35
	v_fma_f32 v36, -v27, v79, v36
	s_waitcnt lgkmcnt(1)
	v_fma_f32 v2, -v28, v144, v2
	v_fma_f32 v3, -v29, v145, v3
	v_fma_f32 v35, -v30, v146, v35
	v_fma_f32 v36, -v31, v147, v36
	s_waitcnt lgkmcnt(0)
	v_fma_f32 v2, -v32, v160, v2
	v_fma_f32 v3, -v33, v161, v3
	v_fma_f32 v35, -v162, v34, v35
	v_add_f32_e32 v2, v3, v2
	v_add_f32_e32 v3, v36, v35
	v_add_f32_e32 v35, v3, v2
	ds_read2st64_b32 v[2:3], v186 offset1:2
	s_waitcnt lgkmcnt(0)
	v_mul_f32_e32 v36, v2, v3
	v_mul_f32_e32 v3, v195, v2
	v_cvt_pk_bf16_f32 v3, v3, v3
	ds_write_b16 v190, v3
	v_mul_f32_e32 v3, v195, v36
	v_cvt_pk_bf16_f32 v3, v3, v3
	ds_write_b16 v190, v3 offset:64
	v_add_u32_e32 v3, v171, v189
	s_and_saveexec_b64 s[18:19], s[8:9]
	ds_write_b16 v3, v227 offset:128
	s_or_b64 exec, exec, s[18:19]
	v_mul_f32_e32 v37, v17, v2
	v_cvt_pk_bf16_f32 v37, v37, v37
	ds_write_b16 v190, v37 offset:272
	v_mul_f32_e32 v37, v17, v36
	v_cvt_pk_bf16_f32 v37, v37, v37
	ds_write_b16 v190, v37 offset:336
	s_and_saveexec_b64 s[18:19], s[8:9]
	v_cvt_pk_bf16_f32 v17, -v17, -v17
	ds_write_b16 v3, v17 offset:400
	s_or_b64 exec, exec, s[18:19]
	v_mul_f32_e32 v17, v15, v2
	v_cvt_pk_bf16_f32 v17, v17, v17
	ds_write_b16 v190, v17 offset:544
	v_mul_f32_e32 v17, v15, v36
	v_cvt_pk_bf16_f32 v17, v17, v17
	ds_write_b16 v190, v17 offset:608
	s_and_saveexec_b64 s[18:19], s[8:9]
	v_cvt_pk_bf16_f32 v15, -v15, -v15
	ds_write_b16 v3, v15 offset:672
	s_or_b64 exec, exec, s[18:19]
	v_mul_f32_e32 v15, v13, v2
	v_cvt_pk_bf16_f32 v15, v15, v15
	ds_write_b16 v190, v15 offset:816
	v_mul_f32_e32 v15, v13, v36
	v_cvt_pk_bf16_f32 v15, v15, v15
	ds_write_b16 v190, v15 offset:880
	s_and_saveexec_b64 s[18:19], s[8:9]
	v_cvt_pk_bf16_f32 v13, -v13, -v13
	ds_write_b16 v3, v13 offset:944
	s_or_b64 exec, exec, s[18:19]
	v_mul_f32_e32 v13, v11, v2
	v_cvt_pk_bf16_f32 v13, v13, v13
	ds_write_b16 v190, v13 offset:1088
	v_mul_f32_e32 v13, v11, v36
	v_cvt_pk_bf16_f32 v13, v13, v13
	ds_write_b16 v190, v13 offset:1152
	s_and_saveexec_b64 s[18:19], s[8:9]
	v_cvt_pk_bf16_f32 v11, -v11, -v11
	ds_write_b16 v3, v11 offset:1216
	s_or_b64 exec, exec, s[18:19]
	v_mul_f32_e32 v11, v9, v2
	v_cvt_pk_bf16_f32 v11, v11, v11
	ds_write_b16 v190, v11 offset:1360
	v_mul_f32_e32 v11, v9, v36
	v_cvt_pk_bf16_f32 v11, v11, v11
	ds_write_b16 v190, v11 offset:1424
	s_and_saveexec_b64 s[18:19], s[8:9]
	v_cvt_pk_bf16_f32 v9, -v9, -v9
	ds_write_b16 v3, v9 offset:1488
	s_or_b64 exec, exec, s[18:19]
	v_mul_f32_e32 v9, v7, v2
	v_cvt_pk_bf16_f32 v9, v9, v9
	ds_write_b16 v190, v9 offset:1632
	v_mul_f32_e32 v9, v7, v36
	v_cvt_pk_bf16_f32 v9, v9, v9
	ds_write_b16 v190, v9 offset:1696
	s_and_saveexec_b64 s[18:19], s[8:9]
	v_cvt_pk_bf16_f32 v7, -v7, -v7
	ds_write_b16 v3, v7 offset:1760
	s_or_b64 exec, exec, s[18:19]
	v_mul_f32_e32 v7, v4, v2
	v_cvt_pk_bf16_f32 v7, v7, v7
	ds_write_b16 v190, v7 offset:1904
	v_mul_f32_e32 v7, v4, v36
	v_cvt_pk_bf16_f32 v7, v7, v7
	ds_write_b16 v190, v7 offset:1968
	s_and_saveexec_b64 s[18:19], s[8:9]
	v_cvt_pk_bf16_f32 v4, -v4, -v4
	ds_write_b16 v3, v4 offset:2032
	s_or_b64 exec, exec, s[18:19]
	v_mul_f32_e32 v4, v5, v2
	v_cvt_pk_bf16_f32 v4, v4, v4
	ds_write_b16 v190, v4 offset:2176
	v_mul_f32_e32 v4, v5, v36
	v_cvt_pk_bf16_f32 v4, v4, v4
	ds_write_b16 v190, v4 offset:2240
	s_and_saveexec_b64 s[18:19], s[8:9]
	v_cvt_pk_bf16_f32 v4, -v5, -v5
	ds_write_b16 v3, v4 offset:2304
	s_or_b64 exec, exec, s[18:19]
	v_mul_f32_e32 v4, v6, v2
	v_cvt_pk_bf16_f32 v4, v4, v4
	ds_write_b16 v190, v4 offset:2448
	v_mul_f32_e32 v4, v6, v36
	v_cvt_pk_bf16_f32 v4, v4, v4
	ds_write_b16 v190, v4 offset:2512
	s_and_saveexec_b64 s[18:19], s[8:9]
	v_cvt_pk_bf16_f32 v4, -v6, -v6
	ds_write_b16 v3, v4 offset:2576
	s_or_b64 exec, exec, s[18:19]
	v_mul_f32_e32 v4, v8, v2
	v_cvt_pk_bf16_f32 v4, v4, v4
	ds_write_b16 v190, v4 offset:2720
	v_mul_f32_e32 v4, v8, v36
	v_cvt_pk_bf16_f32 v4, v4, v4
	ds_write_b16 v190, v4 offset:2784
	s_and_saveexec_b64 s[18:19], s[8:9]
	v_cvt_pk_bf16_f32 v4, -v8, -v8
	ds_write_b16 v3, v4 offset:2848
	s_or_b64 exec, exec, s[18:19]
	v_mul_f32_e32 v4, v10, v2
	v_cvt_pk_bf16_f32 v4, v4, v4
	ds_write_b16 v190, v4 offset:2992
	v_mul_f32_e32 v4, v10, v36
	v_cvt_pk_bf16_f32 v4, v4, v4
	ds_write_b16 v190, v4 offset:3056
	s_and_saveexec_b64 s[18:19], s[8:9]
	v_cvt_pk_bf16_f32 v4, -v10, -v10
	ds_write_b16 v3, v4 offset:3120
	s_or_b64 exec, exec, s[18:19]
	v_mul_f32_e32 v4, v12, v2
	v_cvt_pk_bf16_f32 v4, v4, v4
	ds_write_b16 v190, v4 offset:3264
	v_mul_f32_e32 v4, v12, v36
	v_cvt_pk_bf16_f32 v4, v4, v4
	ds_write_b16 v190, v4 offset:3328
	s_and_saveexec_b64 s[18:19], s[8:9]
	v_cvt_pk_bf16_f32 v4, -v12, -v12
	ds_write_b16 v3, v4 offset:3392
	s_or_b64 exec, exec, s[18:19]
	v_mul_f32_e32 v4, v14, v2
	v_cvt_pk_bf16_f32 v4, v4, v4
	ds_write_b16 v190, v4 offset:3536
	v_mul_f32_e32 v4, v14, v36
	v_cvt_pk_bf16_f32 v4, v4, v4
	ds_write_b16 v190, v4 offset:3600
	s_and_saveexec_b64 s[18:19], s[8:9]
	v_cvt_pk_bf16_f32 v4, -v14, -v14
	ds_write_b16 v3, v4 offset:3664
	s_or_b64 exec, exec, s[18:19]
	v_mul_f32_e32 v4, v16, v2
	v_cvt_pk_bf16_f32 v4, v4, v4
	ds_write_b16 v190, v4 offset:3808
	v_mul_f32_e32 v4, v16, v36
	v_cvt_pk_bf16_f32 v4, v4, v4
	ds_write_b16 v190, v4 offset:3872
	s_and_saveexec_b64 s[18:19], s[8:9]
	v_cvt_pk_bf16_f32 v4, -v16, -v16
	ds_write_b16 v3, v4 offset:3936
	s_or_b64 exec, exec, s[18:19]
	v_mul_f32_e32 v4, v18, v2
	v_cvt_pk_bf16_f32 v4, v4, v4
	ds_write_b16 v190, v4 offset:4080
	v_mul_f32_e32 v4, v18, v36
	v_cvt_pk_bf16_f32 v4, v4, v4
	ds_write_b16 v190, v4 offset:4144
	s_and_saveexec_b64 s[18:19], s[8:9]
	v_cvt_pk_bf16_f32 v4, -v18, -v18
	ds_write_b16 v3, v4 offset:4208
	s_or_b64 exec, exec, s[18:19]
	v_mul_f32_e32 v4, v19, v2
	v_cvt_pk_bf16_f32 v4, v4, v4
	ds_write_b16 v190, v4 offset:4352
	v_mul_f32_e32 v4, v19, v36
	v_cvt_pk_bf16_f32 v4, v4, v4
	ds_write_b16 v190, v4 offset:4416
	s_and_saveexec_b64 s[18:19], s[8:9]
	v_cvt_pk_bf16_f32 v4, -v19, -v19
	ds_write_b16 v3, v4 offset:4480
	s_or_b64 exec, exec, s[18:19]
	v_mul_f32_e32 v4, v20, v2
	v_cvt_pk_bf16_f32 v4, v4, v4
	ds_write_b16 v190, v4 offset:4624
	v_mul_f32_e32 v4, v20, v36
	v_cvt_pk_bf16_f32 v4, v4, v4
	ds_write_b16 v190, v4 offset:4688
	s_and_saveexec_b64 s[18:19], s[8:9]
	v_cvt_pk_bf16_f32 v4, -v20, -v20
	ds_write_b16 v3, v4 offset:4752
	s_or_b64 exec, exec, s[18:19]
	v_mul_f32_e32 v4, v21, v2
	v_cvt_pk_bf16_f32 v4, v4, v4
	ds_write_b16 v190, v4 offset:4896
	v_mul_f32_e32 v4, v21, v36
	v_cvt_pk_bf16_f32 v4, v4, v4
	ds_write_b16 v190, v4 offset:4960
	s_and_saveexec_b64 s[18:19], s[8:9]
	v_cvt_pk_bf16_f32 v4, -v21, -v21
	ds_write_b16 v3, v4 offset:5024
	s_or_b64 exec, exec, s[18:19]
	v_mul_f32_e32 v4, v22, v2
	v_cvt_pk_bf16_f32 v4, v4, v4
	ds_write_b16 v190, v4 offset:5168
	v_mul_f32_e32 v4, v22, v36
	v_cvt_pk_bf16_f32 v4, v4, v4
	ds_write_b16 v190, v4 offset:5232
	s_and_saveexec_b64 s[18:19], s[8:9]
	v_cvt_pk_bf16_f32 v4, -v22, -v22
	ds_write_b16 v3, v4 offset:5296
	s_or_b64 exec, exec, s[18:19]
	v_mul_f32_e32 v4, v23, v2
	v_cvt_pk_bf16_f32 v4, v4, v4
	ds_write_b16 v190, v4 offset:5440
	v_mul_f32_e32 v4, v23, v36
	v_cvt_pk_bf16_f32 v4, v4, v4
	ds_write_b16 v190, v4 offset:5504
	s_and_saveexec_b64 s[18:19], s[8:9]
	v_cvt_pk_bf16_f32 v4, -v23, -v23
	ds_write_b16 v3, v4 offset:5568
	s_or_b64 exec, exec, s[18:19]
	v_mul_f32_e32 v4, v24, v2
	v_cvt_pk_bf16_f32 v4, v4, v4
	ds_write_b16 v190, v4 offset:5712
	v_mul_f32_e32 v4, v24, v36
	v_cvt_pk_bf16_f32 v4, v4, v4
	ds_write_b16 v190, v4 offset:5776
	s_and_saveexec_b64 s[18:19], s[8:9]
	v_cvt_pk_bf16_f32 v4, -v24, -v24
	ds_write_b16 v3, v4 offset:5840
	s_or_b64 exec, exec, s[18:19]
	v_mul_f32_e32 v4, v25, v2
	v_cvt_pk_bf16_f32 v4, v4, v4
	ds_write_b16 v190, v4 offset:5984
	v_mul_f32_e32 v4, v25, v36
	v_cvt_pk_bf16_f32 v4, v4, v4
	ds_write_b16 v190, v4 offset:6048
	s_and_saveexec_b64 s[18:19], s[8:9]
	v_cvt_pk_bf16_f32 v4, -v25, -v25
	ds_write_b16 v3, v4 offset:6112
	s_or_b64 exec, exec, s[18:19]
	v_mul_f32_e32 v4, v27, v2
	v_cvt_pk_bf16_f32 v4, v4, v4
	ds_write_b16 v190, v4 offset:6256
	v_mul_f32_e32 v4, v27, v36
	v_cvt_pk_bf16_f32 v4, v4, v4
	ds_write_b16 v190, v4 offset:6320
	s_and_saveexec_b64 s[18:19], s[8:9]
	v_cvt_pk_bf16_f32 v4, -v27, -v27
	ds_write_b16 v3, v4 offset:6384
	s_or_b64 exec, exec, s[18:19]
	v_mul_f32_e32 v4, v28, v2
	v_cvt_pk_bf16_f32 v4, v4, v4
	ds_write_b16 v190, v4 offset:6528
	v_mul_f32_e32 v4, v28, v36
	v_cvt_pk_bf16_f32 v4, v4, v4
	ds_write_b16 v190, v4 offset:6592
	s_and_saveexec_b64 s[18:19], s[8:9]
	v_cvt_pk_bf16_f32 v4, -v28, -v28
	ds_write_b16 v3, v4 offset:6656
	s_or_b64 exec, exec, s[18:19]
	v_mul_f32_e32 v4, v29, v2
	v_cvt_pk_bf16_f32 v4, v4, v4
	ds_write_b16 v190, v4 offset:6800
	v_mul_f32_e32 v4, v29, v36
	v_cvt_pk_bf16_f32 v4, v4, v4
	ds_write_b16 v190, v4 offset:6864
	s_and_saveexec_b64 s[18:19], s[8:9]
	v_cvt_pk_bf16_f32 v4, -v29, -v29
	ds_write_b16 v3, v4 offset:6928
	s_or_b64 exec, exec, s[18:19]
	v_mul_f32_e32 v4, v30, v2
	v_cvt_pk_bf16_f32 v4, v4, v4
	ds_write_b16 v190, v4 offset:7072
	v_mul_f32_e32 v4, v30, v36
	v_cvt_pk_bf16_f32 v4, v4, v4
	ds_write_b16 v190, v4 offset:7136
	s_and_saveexec_b64 s[18:19], s[8:9]
	v_cvt_pk_bf16_f32 v4, -v30, -v30
	ds_write_b16 v3, v4 offset:7200
	s_or_b64 exec, exec, s[18:19]
	v_mul_f32_e32 v4, v31, v2
	v_cvt_pk_bf16_f32 v4, v4, v4
	ds_write_b16 v190, v4 offset:7344
	v_mul_f32_e32 v4, v31, v36
	v_cvt_pk_bf16_f32 v4, v4, v4
	ds_write_b16 v190, v4 offset:7408
	s_and_saveexec_b64 s[18:19], s[8:9]
	v_cvt_pk_bf16_f32 v4, -v31, -v31
	ds_write_b16 v3, v4 offset:7472
	s_or_b64 exec, exec, s[18:19]
	v_mul_f32_e32 v4, v32, v2
	v_cvt_pk_bf16_f32 v4, v4, v4
	ds_write_b16 v190, v4 offset:7616
	v_mul_f32_e32 v4, v32, v36
	v_cvt_pk_bf16_f32 v4, v4, v4
	ds_write_b16 v190, v4 offset:7680
	s_and_saveexec_b64 s[18:19], s[8:9]
	v_cvt_pk_bf16_f32 v4, -v32, -v32
	ds_write_b16 v3, v4 offset:7744
	s_or_b64 exec, exec, s[18:19]
	v_mul_f32_e32 v4, v33, v2
	v_cvt_pk_bf16_f32 v4, v4, v4
	ds_write_b16 v190, v4 offset:7888
	v_mul_f32_e32 v4, v33, v36
	v_cvt_pk_bf16_f32 v4, v4, v4
	ds_write_b16 v190, v4 offset:7952
	s_and_saveexec_b64 s[18:19], s[8:9]
	v_cvt_pk_bf16_f32 v4, -v33, -v33
	ds_write_b16 v3, v4 offset:8016
	s_or_b64 exec, exec, s[18:19]
	v_mul_f32_e32 v4, v34, v2
	v_cvt_pk_bf16_f32 v4, v4, v4
	ds_write_b16 v190, v4 offset:8160
	v_mul_f32_e32 v4, v34, v36
	v_cvt_pk_bf16_f32 v4, v4, v4
	ds_write_b16 v190, v4 offset:8224
	s_and_saveexec_b64 s[18:19], s[8:9]
	v_cvt_pk_bf16_f32 v4, -v34, -v34
	ds_write_b16 v3, v4 offset:8288
	s_or_b64 exec, exec, s[18:19]
	v_mul_f32_e32 v2, v35, v2
	v_cvt_pk_bf16_f32 v2, v2, v2
	ds_write_b16 v190, v2 offset:8432
	v_mul_f32_e32 v2, v35, v36
	v_cvt_pk_bf16_f32 v2, v2, v2
	ds_write_b16 v190, v2 offset:8496
	s_and_saveexec_b64 s[18:19], s[8:9]
	v_cvt_pk_bf16_f32 v2, -v35, -v35
	ds_write_b16 v3, v2 offset:8560
	s_or_b64 exec, exec, s[18:19]
